# FFN-up HID stores back to plain (no leader flush at group seams, write-through acks no longer pay)
# baseline (speedup 1.0000x reference)
.LBB0_1203:
	ds_read_b128 v[150:153], v147
	ds_read_b128 v[154:157], v147 offset:1024
	ds_read_b128 v[158:161], v147 offset:2048
	ds_read_b128 v[162:165], v147 offset:3072
	s_add_u32 s36, s34, 0xfff80080
	s_addc_u32 s37, s35, -1
	s_cmp_eq_u32 s60, 28
	s_cselect_b32 s39, s13, s37
	s_cselect_b32 s38, s58, s36
	s_cselect_b32 s37, s11, s59
	s_cselect_b32 s36, s28, s29
	s_add_i32 m0, s31, 0xc000
	ds_read_b128 v[166:169], v148
	ds_read_b128 v[170:173], v148 offset:1024
	ds_read_b128 v[174:177], v148 offset:2048
	ds_read_b128 v[178:181], v148 offset:3072
	ds_read_b128 v[182:185], v148 offset:4096
	ds_read_b128 v[186:189], v148 offset:5120
	ds_read_b128 v[190:193], v148 offset:6144
	ds_read_b128 v[194:197], v148 offset:7168
	global_load_lds_dwordx4 v136, s[34:35]
	s_add_i32 m0, s31, 0xe000
	s_nop 0
	global_load_lds_dwordx4 v138, s[34:35]
	s_waitcnt lgkmcnt(8)
	s_barrier
	s_waitcnt lgkmcnt(0)
	v_mfma_f32_16x16x32_bf16 v[124:127], v[150:153], v[166:169], v[124:127]
	v_mfma_f32_16x16x32_bf16 v[120:123], v[158:161], v[166:169], v[120:123]
	v_mfma_f32_16x16x32_bf16 v[108:111], v[150:153], v[174:177], v[108:111]
	v_mfma_f32_16x16x32_bf16 v[104:107], v[158:161], v[174:177], v[104:107]
	v_mfma_f32_16x16x32_bf16 v[92:95], v[150:153], v[182:185], v[92:95]
	v_mfma_f32_16x16x32_bf16 v[88:91], v[158:161], v[182:185], v[88:91]
	v_mfma_f32_16x16x32_bf16 v[76:79], v[150:153], v[190:193], v[76:79]
	v_mfma_f32_16x16x32_bf16 v[72:75], v[158:161], v[190:193], v[72:75]
	v_mfma_f32_16x16x32_bf16 v[124:127], v[154:157], v[170:173], v[124:127]
	v_mfma_f32_16x16x32_bf16 v[120:123], v[162:165], v[170:173], v[120:123]
	v_mfma_f32_16x16x32_bf16 v[108:111], v[154:157], v[178:181], v[108:111]
	v_mfma_f32_16x16x32_bf16 v[104:107], v[162:165], v[178:181], v[104:107]
	v_mfma_f32_16x16x32_bf16 v[92:95], v[154:157], v[186:189], v[92:95]
	v_mfma_f32_16x16x32_bf16 v[88:91], v[162:165], v[186:189], v[88:91]
	v_mfma_f32_16x16x32_bf16 v[76:79], v[154:157], v[194:197], v[76:79]
	v_mfma_f32_16x16x32_bf16 v[72:75], v[162:165], v[194:197], v[72:75]
	s_barrier
	s_add_i32 s61, s54, s43
	s_add_u32 s98, s36, s8
	s_addc_u32 s99, s37, s9
	s_mov_b32 m0, s61
	ds_read_b128 v[198:201], v149
	ds_read_b128 v[202:205], v149 offset:1024
	ds_read_b128 v[206:209], v149 offset:2048
	ds_read_b128 v[210:213], v149 offset:3072
	global_load_lds_dwordx4 v132, s[36:37]
	s_add_i32 m0, s61, 0x2000
	s_nop 0
	global_load_lds_dwordx4 v128, s[36:37]
	s_barrier
	s_waitcnt lgkmcnt(0)
	v_mfma_f32_16x16x32_bf16 v[116:119], v[198:201], v[166:169], v[116:119]
	v_mfma_f32_16x16x32_bf16 v[112:115], v[206:209], v[166:169], v[112:115]
	v_mfma_f32_16x16x32_bf16 v[100:103], v[198:201], v[174:177], v[100:103]
	v_mfma_f32_16x16x32_bf16 v[96:99], v[206:209], v[174:177], v[96:99]
	v_mfma_f32_16x16x32_bf16 v[84:87], v[198:201], v[182:185], v[84:87]
	v_mfma_f32_16x16x32_bf16 v[80:83], v[206:209], v[182:185], v[80:83]
	v_mfma_f32_16x16x32_bf16 v[68:71], v[198:201], v[190:193], v[68:71]
	v_mfma_f32_16x16x32_bf16 v[64:67], v[206:209], v[190:193], v[64:67]
	v_mfma_f32_16x16x32_bf16 v[116:119], v[202:205], v[170:173], v[116:119]
	v_mfma_f32_16x16x32_bf16 v[112:115], v[210:213], v[170:173], v[112:115]
	v_mfma_f32_16x16x32_bf16 v[100:103], v[202:205], v[178:181], v[100:103]
	v_mfma_f32_16x16x32_bf16 v[96:99], v[210:213], v[178:181], v[96:99]
	v_mfma_f32_16x16x32_bf16 v[84:87], v[202:205], v[186:189], v[84:87]
	v_mfma_f32_16x16x32_bf16 v[80:83], v[210:213], v[186:189], v[80:83]
	v_mfma_f32_16x16x32_bf16 v[68:71], v[202:205], v[194:197], v[68:71]
	v_mfma_f32_16x16x32_bf16 v[64:67], v[210:213], v[194:197], v[64:67]
	s_mov_b32 m0, s31
	s_add_u32 s100, s38, s8
	s_addc_u32 s101, s39, s9
	s_barrier
	ds_read_b128 v[166:169], v148 offset:16384
	ds_read_b128 v[170:173], v148 offset:17408
	ds_read_b128 v[174:177], v148 offset:18432
	ds_read_b128 v[178:181], v148 offset:19456
	ds_read_b128 v[182:185], v148 offset:20480
	ds_read_b128 v[186:189], v148 offset:21504
	ds_read_b128 v[190:193], v148 offset:22528
	ds_read_b128 v[194:197], v148 offset:23552
	global_load_lds_dwordx4 v134, s[38:39]
	s_mov_b32 m0, s46
	s_nop 0
	global_load_lds_dwordx4 v130, s[38:39]
	s_barrier
	s_waitcnt lgkmcnt(0)
	v_mfma_f32_16x16x32_bf16 v[60:63], v[150:153], v[166:169], v[60:63]
	v_mfma_f32_16x16x32_bf16 v[56:59], v[158:161], v[166:169], v[56:59]
	v_mfma_f32_16x16x32_bf16 v[44:47], v[150:153], v[174:177], v[44:47]
	v_mfma_f32_16x16x32_bf16 v[40:43], v[158:161], v[174:177], v[40:43]
	v_mfma_f32_16x16x32_bf16 v[28:31], v[150:153], v[182:185], v[28:31]
	v_mfma_f32_16x16x32_bf16 v[24:27], v[158:161], v[182:185], v[24:27]
	v_mfma_f32_16x16x32_bf16 v[12:15], v[150:153], v[190:193], v[12:15]
	v_mfma_f32_16x16x32_bf16 v[8:11], v[158:161], v[190:193], v[8:11]
	v_mfma_f32_16x16x32_bf16 v[60:63], v[154:157], v[170:173], v[60:63]
	v_mfma_f32_16x16x32_bf16 v[56:59], v[162:165], v[170:173], v[56:59]
	v_mfma_f32_16x16x32_bf16 v[44:47], v[154:157], v[178:181], v[44:47]
	v_mfma_f32_16x16x32_bf16 v[40:43], v[162:165], v[178:181], v[40:43]
	v_mfma_f32_16x16x32_bf16 v[28:31], v[154:157], v[186:189], v[28:31]
	v_mfma_f32_16x16x32_bf16 v[24:27], v[162:165], v[186:189], v[24:27]
	v_mfma_f32_16x16x32_bf16 v[12:15], v[154:157], v[194:197], v[12:15]
	v_mfma_f32_16x16x32_bf16 v[8:11], v[162:165], v[194:197], v[8:11]
	s_barrier
	s_add_u32 s62, s36, 0x80000
	s_addc_u32 s63, s37, 0
	s_add_i32 s61, s55, s43
	s_mov_b32 m0, s61
	s_nop 0
	global_load_lds_dwordx4 v132, s[62:63]
	s_add_i32 m0, s61, 0x2000
	s_nop 0
	global_load_lds_dwordx4 v128, s[62:63]
	s_waitcnt vmcnt(6)
	s_barrier
	v_mfma_f32_16x16x32_bf16 v[52:55], v[198:201], v[166:169], v[52:55]
	v_mfma_f32_16x16x32_bf16 v[48:51], v[206:209], v[166:169], v[48:51]
	v_mfma_f32_16x16x32_bf16 v[36:39], v[198:201], v[174:177], v[36:39]
	v_mfma_f32_16x16x32_bf16 v[32:35], v[206:209], v[174:177], v[32:35]
	v_mfma_f32_16x16x32_bf16 v[20:23], v[198:201], v[182:185], v[20:23]
	v_mfma_f32_16x16x32_bf16 v[16:19], v[206:209], v[182:185], v[16:19]
	v_mfma_f32_16x16x32_bf16 v[4:7], v[198:201], v[190:193], v[4:7]
	v_mfma_f32_16x16x32_bf16 v[0:3], v[206:209], v[190:193], v[0:3]
	v_mfma_f32_16x16x32_bf16 v[52:55], v[202:205], v[170:173], v[52:55]
	v_mfma_f32_16x16x32_bf16 v[48:51], v[210:213], v[170:173], v[48:51]
	v_mfma_f32_16x16x32_bf16 v[36:39], v[202:205], v[178:181], v[36:39]
	v_mfma_f32_16x16x32_bf16 v[32:35], v[210:213], v[178:181], v[32:35]
	v_mfma_f32_16x16x32_bf16 v[20:23], v[202:205], v[186:189], v[20:23]
	v_mfma_f32_16x16x32_bf16 v[16:19], v[210:213], v[186:189], v[16:19]
	v_mfma_f32_16x16x32_bf16 v[4:7], v[202:205], v[194:197], v[4:7]
	v_mfma_f32_16x16x32_bf16 v[0:3], v[210:213], v[194:197], v[0:3]
	s_add_i32 s61, 0, 0x18000
	s_barrier
	ds_read_b128 v[150:153], v244
	ds_read_b128 v[154:157], v244 offset:1024
	ds_read_b128 v[158:161], v244 offset:2048
	ds_read_b128 v[162:165], v244 offset:3072
	s_add_u32 s38, s38, 0x80000
	s_addc_u32 s39, s39, 0
	s_mov_b32 m0, s47
	ds_read_b128 v[166:169], v148 offset:32768
	ds_read_b128 v[170:173], v148 offset:33792
	ds_read_b128 v[174:177], v148 offset:34816
	ds_read_b128 v[178:181], v148 offset:35840
	ds_read_b128 v[182:185], v148 offset:36864
	ds_read_b128 v[186:189], v148 offset:37888
	ds_read_b128 v[190:193], v148 offset:38912
	ds_read_b128 v[194:197], v148 offset:39936
	global_load_lds_dwordx4 v134, s[38:39]
	s_mov_b32 m0, s48
	s_nop 0
	global_load_lds_dwordx4 v130, s[38:39]
	s_waitcnt lgkmcnt(8)
	s_barrier
	s_waitcnt lgkmcnt(0)
	v_mfma_f32_16x16x32_bf16 v[124:127], v[150:153], v[166:169], v[124:127]
	v_mfma_f32_16x16x32_bf16 v[120:123], v[158:161], v[166:169], v[120:123]
	v_mfma_f32_16x16x32_bf16 v[108:111], v[150:153], v[174:177], v[108:111]
	v_mfma_f32_16x16x32_bf16 v[104:107], v[158:161], v[174:177], v[104:107]
	v_mfma_f32_16x16x32_bf16 v[92:95], v[150:153], v[182:185], v[92:95]
	v_mfma_f32_16x16x32_bf16 v[88:91], v[158:161], v[182:185], v[88:91]
	v_mfma_f32_16x16x32_bf16 v[76:79], v[150:153], v[190:193], v[76:79]
	v_mfma_f32_16x16x32_bf16 v[72:75], v[158:161], v[190:193], v[72:75]
	v_mfma_f32_16x16x32_bf16 v[124:127], v[154:157], v[170:173], v[124:127]
	v_mfma_f32_16x16x32_bf16 v[120:123], v[162:165], v[170:173], v[120:123]
	v_mfma_f32_16x16x32_bf16 v[108:111], v[154:157], v[178:181], v[108:111]
	v_mfma_f32_16x16x32_bf16 v[104:107], v[162:165], v[178:181], v[104:107]
	v_mfma_f32_16x16x32_bf16 v[92:95], v[154:157], v[186:189], v[92:95]
	v_mfma_f32_16x16x32_bf16 v[88:91], v[162:165], v[186:189], v[88:91]
	v_mfma_f32_16x16x32_bf16 v[76:79], v[154:157], v[194:197], v[76:79]
	v_mfma_f32_16x16x32_bf16 v[72:75], v[162:165], v[194:197], v[72:75]
	s_barrier
	s_add_i32 s38, 0, 0x1c000
	s_add_i32 s39, s61, s43
	s_mov_b32 m0, s39
	ds_read_b128 v[198:201], v245
	ds_read_b128 v[202:205], v245 offset:1024
	ds_read_b128 v[206:209], v245 offset:2048
	ds_read_b128 v[210:213], v245 offset:3072
	global_load_lds_dwordx4 v132, s[98:99]
	s_add_i32 m0, s39, 0x2000
	s_nop 0
	global_load_lds_dwordx4 v128, s[98:99]
	s_barrier
	s_waitcnt lgkmcnt(0)
	v_mfma_f32_16x16x32_bf16 v[116:119], v[198:201], v[166:169], v[116:119]
	v_mfma_f32_16x16x32_bf16 v[112:115], v[206:209], v[166:169], v[112:115]
	v_mfma_f32_16x16x32_bf16 v[100:103], v[198:201], v[174:177], v[100:103]
	v_mfma_f32_16x16x32_bf16 v[96:99], v[206:209], v[174:177], v[96:99]
	v_mfma_f32_16x16x32_bf16 v[84:87], v[198:201], v[182:185], v[84:87]
	v_mfma_f32_16x16x32_bf16 v[80:83], v[206:209], v[182:185], v[80:83]
	v_mfma_f32_16x16x32_bf16 v[68:71], v[198:201], v[190:193], v[68:71]
	v_mfma_f32_16x16x32_bf16 v[64:67], v[206:209], v[190:193], v[64:67]
	v_mfma_f32_16x16x32_bf16 v[116:119], v[202:205], v[170:173], v[116:119]
	v_mfma_f32_16x16x32_bf16 v[112:115], v[210:213], v[170:173], v[112:115]
	v_mfma_f32_16x16x32_bf16 v[100:103], v[202:205], v[178:181], v[100:103]
	v_mfma_f32_16x16x32_bf16 v[96:99], v[210:213], v[178:181], v[96:99]
	v_mfma_f32_16x16x32_bf16 v[84:87], v[202:205], v[186:189], v[84:87]
	v_mfma_f32_16x16x32_bf16 v[80:83], v[210:213], v[186:189], v[80:83]
	v_mfma_f32_16x16x32_bf16 v[68:71], v[202:205], v[194:197], v[68:71]
	v_mfma_f32_16x16x32_bf16 v[64:67], v[210:213], v[194:197], v[64:67]
	s_mov_b32 m0, s50
	s_barrier
	ds_read_b128 v[166:169], v148 offset:49152
	ds_read_b128 v[170:173], v148 offset:50176
	ds_read_b128 v[174:177], v148 offset:51200
	ds_read_b128 v[178:181], v148 offset:52224
	ds_read_b128 v[182:185], v148 offset:53248
	ds_read_b128 v[186:189], v148 offset:54272
	ds_read_b128 v[190:193], v148 offset:55296
	ds_read_b128 v[194:197], v148 offset:56320
	global_load_lds_dwordx4 v134, s[100:101]
	s_mov_b32 m0, s51
	s_nop 0
	global_load_lds_dwordx4 v130, s[100:101]
	s_barrier
	s_waitcnt lgkmcnt(0)
	v_mfma_f32_16x16x32_bf16 v[60:63], v[150:153], v[166:169], v[60:63]
	v_mfma_f32_16x16x32_bf16 v[56:59], v[158:161], v[166:169], v[56:59]
	v_mfma_f32_16x16x32_bf16 v[44:47], v[150:153], v[174:177], v[44:47]
	v_mfma_f32_16x16x32_bf16 v[40:43], v[158:161], v[174:177], v[40:43]
	v_mfma_f32_16x16x32_bf16 v[28:31], v[150:153], v[182:185], v[28:31]
	v_mfma_f32_16x16x32_bf16 v[24:27], v[158:161], v[182:185], v[24:27]
	v_mfma_f32_16x16x32_bf16 v[12:15], v[150:153], v[190:193], v[12:15]
	v_mfma_f32_16x16x32_bf16 v[8:11], v[158:161], v[190:193], v[8:11]
	v_mfma_f32_16x16x32_bf16 v[60:63], v[154:157], v[170:173], v[60:63]
	v_mfma_f32_16x16x32_bf16 v[56:59], v[162:165], v[170:173], v[56:59]
	v_mfma_f32_16x16x32_bf16 v[44:47], v[154:157], v[178:181], v[44:47]
	v_mfma_f32_16x16x32_bf16 v[40:43], v[162:165], v[178:181], v[40:43]
	v_mfma_f32_16x16x32_bf16 v[28:31], v[154:157], v[186:189], v[28:31]
	v_mfma_f32_16x16x32_bf16 v[24:27], v[162:165], v[186:189], v[24:27]
	v_mfma_f32_16x16x32_bf16 v[12:15], v[154:157], v[194:197], v[12:15]
	v_mfma_f32_16x16x32_bf16 v[8:11], v[162:165], v[194:197], v[8:11]
	s_barrier
	s_add_u32 s36, s36, 0x80080
	s_addc_u32 s37, s37, 0
	s_add_i32 s38, s38, s43
	s_mov_b32 m0, s38
	s_nop 0
	global_load_lds_dwordx4 v132, s[36:37]
	s_add_i32 m0, s38, 0x2000
	s_nop 0
	global_load_lds_dwordx4 v128, s[36:37]
	s_waitcnt vmcnt(6)
	s_barrier
	v_mfma_f32_16x16x32_bf16 v[52:55], v[198:201], v[166:169], v[52:55]
	v_mfma_f32_16x16x32_bf16 v[48:51], v[206:209], v[166:169], v[48:51]
	v_mfma_f32_16x16x32_bf16 v[36:39], v[198:201], v[174:177], v[36:39]
	v_mfma_f32_16x16x32_bf16 v[32:35], v[206:209], v[174:177], v[32:35]
	v_mfma_f32_16x16x32_bf16 v[20:23], v[198:201], v[182:185], v[20:23]
	v_mfma_f32_16x16x32_bf16 v[16:19], v[206:209], v[182:185], v[16:19]
	v_mfma_f32_16x16x32_bf16 v[4:7], v[198:201], v[190:193], v[4:7]
	v_mfma_f32_16x16x32_bf16 v[0:3], v[206:209], v[190:193], v[0:3]
	v_mfma_f32_16x16x32_bf16 v[52:55], v[202:205], v[170:173], v[52:55]
	v_mfma_f32_16x16x32_bf16 v[48:51], v[210:213], v[170:173], v[48:51]
	v_mfma_f32_16x16x32_bf16 v[36:39], v[202:205], v[178:181], v[36:39]
	v_mfma_f32_16x16x32_bf16 v[32:35], v[210:213], v[178:181], v[32:35]
	v_mfma_f32_16x16x32_bf16 v[20:23], v[202:205], v[186:189], v[20:23]
	v_mfma_f32_16x16x32_bf16 v[16:19], v[210:213], v[186:189], v[16:19]
	v_mfma_f32_16x16x32_bf16 v[4:7], v[202:205], v[194:197], v[4:7]
	v_mfma_f32_16x16x32_bf16 v[0:3], v[210:213], v[194:197], v[0:3]
	s_add_i32 s60, s60, 2
	s_add_u32 s34, s34, 0x100
	s_addc_u32 s35, s35, 0
	s_add_u32 s29, s29, 0x100
	s_addc_u32 s59, s59, 0
	s_cmp_gt_u32 s60, 29
	s_barrier
	s_cbranch_scc0 .LBB0_1203
	v_pk_add_f32 v[124:125], v[124:125], 0 op_sel_hi:[1,0]
	v_pk_add_f32 v[126:127], v[126:127], 0 op_sel_hi:[1,0]
	v_mul_f32_e32 v151, 0xbfb8aa3b, v124
	v_exp_f32_e32 v151, v151
	v_mul_f32_e32 v154, 0xbfb8aa3b, v125
	v_exp_f32_e32 v155, v154
	v_pk_add_f32 v[116:117], v[116:117], 0 op_sel_hi:[1,0]
	v_add_f32_e32 v151, 1.0, v151
	v_rcp_f32_e32 v154, v151
	v_add_f32_e32 v151, 1.0, v155
	v_mul_f32_e32 v155, 0xbfb8aa3b, v126
	v_exp_f32_e32 v156, v155
	v_mul_f32_e32 v155, 0xbfb8aa3b, v127
	v_exp_f32_e32 v157, v155
	v_rcp_f32_e32 v155, v151
	v_add_f32_e32 v151, 1.0, v156
	v_rcp_f32_e32 v156, v151
	v_add_f32_e32 v151, 1.0, v157
	v_rcp_f32_e32 v157, v151
	v_pk_mul_f32 v[124:125], v[124:125], v[154:155]
	v_pk_add_f32 v[120:121], v[120:121], 0 op_sel_hi:[1,0]
	v_pk_mul_f32 v[116:117], v[124:125], v[116:117]
	v_pk_mul_f32 v[124:125], v[126:127], v[156:157]
	v_mul_f32_e32 v126, 0xbfb8aa3b, v120
	v_exp_f32_e32 v126, v126
	v_pk_add_f32 v[118:119], v[118:119], 0 op_sel_hi:[1,0]
	v_pk_add_f32 v[122:123], v[122:123], 0 op_sel_hi:[1,0]
	v_pk_mul_f32 v[118:119], v[124:125], v[118:119]
	v_mul_f32_e32 v124, 0xbfb8aa3b, v121
	v_exp_f32_e32 v125, v124
	v_add_f32_e32 v124, 1.0, v126
	v_mul_f32_e32 v126, 0xbfb8aa3b, v122
	v_mul_f32_e32 v127, 0xbfb8aa3b, v123
	v_exp_f32_e32 v126, v126
	v_exp_f32_e32 v127, v127
	v_add_f32_e32 v125, 1.0, v125
	v_rcp_f32_e32 v124, v124
	v_rcp_f32_e32 v125, v125
	v_add_f32_e32 v126, 1.0, v126
	v_add_f32_e32 v127, 1.0, v127
	v_rcp_f32_e32 v126, v126
	v_rcp_f32_e32 v127, v127
	v_pk_add_f32 v[112:113], v[112:113], 0 op_sel_hi:[1,0]
	v_pk_mul_f32 v[120:121], v[120:121], v[124:125]
	v_lshl_or_b32 v152, s57, 7, v146
	v_pk_mul_f32 v[112:113], v[120:121], v[112:113]
	v_pk_add_f32 v[114:115], v[114:115], 0 op_sel_hi:[1,0]
	v_pk_mul_f32 v[120:121], v[122:123], v[126:127]
	v_lshl_add_u32 v150, s30, 8, v142
	v_ashrrev_i32_e32 v153, 31, v152
	v_pk_mul_f32 v[114:115], v[120:121], v[114:115]
	v_cvt_pk_bf16_f32 v116, v116, v117
	v_cvt_pk_bf16_f32 v117, v118, v119
	v_cvt_pk_bf16_f32 v118, v112, v113
	v_mov_b64_e32 v[112:113], s[6:7]
	v_cvt_pk_bf16_f32 v119, v114, v115
	v_mad_i64_i32 v[120:121], s[28:29], v150, s56, v[112:113]
	v_lshlrev_b64 v[114:115], 1, v[152:153]
	v_lshl_add_u64 v[120:121], v[120:121], 0, v[114:115]
	v_pk_add_f32 v[108:109], v[108:109], 0 op_sel_hi:[1,0]
	global_store_dwordx4 v[120:121], v[116:119], off
	v_mul_f32_e32 v122, 0xbfb8aa3b, v108
	v_pk_add_f32 v[110:111], v[110:111], 0 op_sel_hi:[1,0]
	v_mul_f32_e32 v116, 0xbfb8aa3b, v109
	v_exp_f32_e32 v122, v122
	v_exp_f32_e32 v117, v116
	v_mul_f32_e32 v118, 0xbfb8aa3b, v110
	v_mul_f32_e32 v119, 0xbfb8aa3b, v111
	v_exp_f32_e32 v118, v118
	v_exp_f32_e32 v119, v119
	v_add_f32_e32 v116, 1.0, v122
	v_add_f32_e32 v117, 1.0, v117
	v_rcp_f32_e32 v116, v116
	v_rcp_f32_e32 v117, v117
	v_add_f32_e32 v118, 1.0, v118
	v_add_f32_e32 v119, 1.0, v119
	v_rcp_f32_e32 v118, v118
	v_rcp_f32_e32 v119, v119
	v_pk_add_f32 v[100:101], v[100:101], 0 op_sel_hi:[1,0]
	v_pk_mul_f32 v[108:109], v[108:109], v[116:117]
	v_pk_add_f32 v[104:105], v[104:105], 0 op_sel_hi:[1,0]
	v_pk_mul_f32 v[100:101], v[108:109], v[100:101]
	v_pk_mul_f32 v[108:109], v[110:111], v[118:119]
	v_mul_f32_e32 v110, 0xbfb8aa3b, v104
	v_exp_f32_e32 v110, v110
	v_pk_add_f32 v[102:103], v[102:103], 0 op_sel_hi:[1,0]
	v_pk_add_f32 v[106:107], v[106:107], 0 op_sel_hi:[1,0]
	v_pk_mul_f32 v[102:103], v[108:109], v[102:103]
	v_mul_f32_e32 v108, 0xbfb8aa3b, v105
	v_exp_f32_e32 v109, v108
	v_add_f32_e32 v108, 1.0, v110
	v_mul_f32_e32 v110, 0xbfb8aa3b, v106
	v_mul_f32_e32 v111, 0xbfb8aa3b, v107
	v_exp_f32_e32 v110, v110
	v_exp_f32_e32 v111, v111
	v_add_f32_e32 v109, 1.0, v109
	v_rcp_f32_e32 v108, v108
	v_rcp_f32_e32 v109, v109
	v_add_f32_e32 v110, 1.0, v110
	v_add_f32_e32 v111, 1.0, v111
	v_rcp_f32_e32 v110, v110
	v_rcp_f32_e32 v111, v111
	v_pk_add_f32 v[96:97], v[96:97], 0 op_sel_hi:[1,0]
	v_pk_mul_f32 v[104:105], v[104:105], v[108:109]
	v_or_b32_e32 v108, 16, v150
	v_pk_mul_f32 v[104:105], v[104:105], v[96:97]
	v_pk_add_f32 v[96:97], v[98:99], 0 op_sel_hi:[1,0]
	v_pk_mul_f32 v[98:99], v[106:107], v[110:111]
	v_pk_add_f32 v[92:93], v[92:93], 0 op_sel_hi:[1,0]
	v_pk_mul_f32 v[106:107], v[98:99], v[96:97]
	v_cvt_pk_bf16_f32 v96, v100, v101
	v_mad_i64_i32 v[100:101], s[28:29], v108, s56, v[112:113]
	v_cvt_pk_bf16_f32 v97, v102, v103
	v_cvt_pk_bf16_f32 v98, v104, v105
	v_cvt_pk_bf16_f32 v99, v106, v107
	v_lshl_add_u64 v[100:101], v[100:101], 0, v[114:115]
	v_mul_f32_e32 v102, 0xbfb8aa3b, v92
	global_store_dwordx4 v[100:101], v[96:99], off
	v_pk_add_f32 v[94:95], v[94:95], 0 op_sel_hi:[1,0]
	v_exp_f32_e32 v102, v102
	v_mul_f32_e32 v96, 0xbfb8aa3b, v93
	v_exp_f32_e32 v97, v96
	v_mul_f32_e32 v98, 0xbfb8aa3b, v94
	v_mul_f32_e32 v99, 0xbfb8aa3b, v95
	v_exp_f32_e32 v98, v98
	v_exp_f32_e32 v99, v99
	v_add_f32_e32 v96, 1.0, v102
	v_add_f32_e32 v97, 1.0, v97
	v_rcp_f32_e32 v96, v96
	v_rcp_f32_e32 v97, v97
	v_add_f32_e32 v98, 1.0, v98
	v_add_f32_e32 v99, 1.0, v99
	v_rcp_f32_e32 v98, v98
	v_rcp_f32_e32 v99, v99
	v_pk_add_f32 v[84:85], v[84:85], 0 op_sel_hi:[1,0]
	v_pk_mul_f32 v[92:93], v[92:93], v[96:97]
	v_pk_add_f32 v[88:89], v[88:89], 0 op_sel_hi:[1,0]
	v_pk_mul_f32 v[84:85], v[92:93], v[84:85]
	v_pk_mul_f32 v[92:93], v[94:95], v[98:99]
	v_mul_f32_e32 v94, 0xbfb8aa3b, v88
	v_exp_f32_e32 v94, v94
	v_pk_add_f32 v[86:87], v[86:87], 0 op_sel_hi:[1,0]
	v_pk_add_f32 v[90:91], v[90:91], 0 op_sel_hi:[1,0]
	v_pk_mul_f32 v[86:87], v[92:93], v[86:87]
	v_mul_f32_e32 v92, 0xbfb8aa3b, v89
	v_exp_f32_e32 v93, v92
	v_add_f32_e32 v92, 1.0, v94
	v_mul_f32_e32 v94, 0xbfb8aa3b, v90
	v_mul_f32_e32 v95, 0xbfb8aa3b, v91
	v_exp_f32_e32 v94, v94
	v_exp_f32_e32 v95, v95
	v_add_f32_e32 v93, 1.0, v93
	v_rcp_f32_e32 v92, v92
	v_rcp_f32_e32 v93, v93
	v_add_f32_e32 v94, 1.0, v94
	v_add_f32_e32 v95, 1.0, v95
	v_rcp_f32_e32 v94, v94
	v_rcp_f32_e32 v95, v95
	v_pk_add_f32 v[80:81], v[80:81], 0 op_sel_hi:[1,0]
	v_pk_mul_f32 v[88:89], v[88:89], v[92:93]
	v_or_b32_e32 v92, 32, v150
	v_pk_mul_f32 v[88:89], v[88:89], v[80:81]
	v_pk_add_f32 v[80:81], v[82:83], 0 op_sel_hi:[1,0]
	v_pk_mul_f32 v[82:83], v[90:91], v[94:95]
	v_pk_add_f32 v[76:77], v[76:77], 0 op_sel_hi:[1,0]
	v_pk_mul_f32 v[90:91], v[82:83], v[80:81]
	v_cvt_pk_bf16_f32 v80, v84, v85
	v_mad_i64_i32 v[84:85], s[28:29], v92, s56, v[112:113]
	v_cvt_pk_bf16_f32 v81, v86, v87
	v_cvt_pk_bf16_f32 v82, v88, v89
	v_cvt_pk_bf16_f32 v83, v90, v91
	v_lshl_add_u64 v[84:85], v[84:85], 0, v[114:115]
	v_mul_f32_e32 v86, 0xbfb8aa3b, v76
	global_store_dwordx4 v[84:85], v[80:83], off
	v_pk_add_f32 v[78:79], v[78:79], 0 op_sel_hi:[1,0]
	v_exp_f32_e32 v86, v86
	v_mul_f32_e32 v80, 0xbfb8aa3b, v77
	v_exp_f32_e32 v81, v80
	v_mul_f32_e32 v82, 0xbfb8aa3b, v78
	v_mul_f32_e32 v83, 0xbfb8aa3b, v79
	v_exp_f32_e32 v82, v82
	v_exp_f32_e32 v83, v83
	v_add_f32_e32 v80, 1.0, v86
	v_add_f32_e32 v81, 1.0, v81
	v_rcp_f32_e32 v80, v80
	v_rcp_f32_e32 v81, v81
	v_add_f32_e32 v82, 1.0, v82
	v_add_f32_e32 v83, 1.0, v83
	v_rcp_f32_e32 v82, v82
	v_rcp_f32_e32 v83, v83
	v_pk_add_f32 v[68:69], v[68:69], 0 op_sel_hi:[1,0]
	v_pk_mul_f32 v[76:77], v[76:77], v[80:81]
	v_pk_add_f32 v[72:73], v[72:73], 0 op_sel_hi:[1,0]
	v_pk_mul_f32 v[68:69], v[76:77], v[68:69]
	v_pk_mul_f32 v[76:77], v[78:79], v[82:83]
	v_mul_f32_e32 v78, 0xbfb8aa3b, v72
	v_exp_f32_e32 v78, v78
	v_pk_add_f32 v[70:71], v[70:71], 0 op_sel_hi:[1,0]
	v_pk_add_f32 v[74:75], v[74:75], 0 op_sel_hi:[1,0]
	v_pk_mul_f32 v[70:71], v[76:77], v[70:71]
	v_mul_f32_e32 v76, 0xbfb8aa3b, v73
	v_exp_f32_e32 v77, v76
	v_add_f32_e32 v76, 1.0, v78
	v_mul_f32_e32 v78, 0xbfb8aa3b, v74
	v_mul_f32_e32 v79, 0xbfb8aa3b, v75
	v_exp_f32_e32 v78, v78
	v_exp_f32_e32 v79, v79
	v_add_f32_e32 v77, 1.0, v77
	v_rcp_f32_e32 v76, v76
	v_rcp_f32_e32 v77, v77
	v_add_f32_e32 v78, 1.0, v78
	v_add_f32_e32 v79, 1.0, v79
	v_rcp_f32_e32 v78, v78
	v_rcp_f32_e32 v79, v79
	v_pk_add_f32 v[64:65], v[64:65], 0 op_sel_hi:[1,0]
	v_pk_mul_f32 v[72:73], v[72:73], v[76:77]
	v_or_b32_e32 v76, 48, v150
	v_pk_mul_f32 v[72:73], v[72:73], v[64:65]
	v_pk_add_f32 v[64:65], v[66:67], 0 op_sel_hi:[1,0]
	v_pk_mul_f32 v[66:67], v[74:75], v[78:79]
	v_pk_add_f32 v[60:61], v[60:61], 0 op_sel_hi:[1,0]
	v_pk_mul_f32 v[74:75], v[66:67], v[64:65]
	v_cvt_pk_bf16_f32 v64, v68, v69
	v_mad_i64_i32 v[68:69], s[28:29], v76, s56, v[112:113]
	v_cvt_pk_bf16_f32 v65, v70, v71
	v_cvt_pk_bf16_f32 v66, v72, v73
	v_cvt_pk_bf16_f32 v67, v74, v75
	v_lshl_add_u64 v[68:69], v[68:69], 0, v[114:115]
	global_store_dwordx4 v[68:69], v[64:67], off
	v_pk_add_f32 v[62:63], v[62:63], 0 op_sel_hi:[1,0]
	v_pk_add_f32 v[52:53], v[52:53], 0 op_sel_hi:[1,0]
	v_mul_f32_e32 v64, 0xbfb8aa3b, v60
	v_mul_f32_e32 v65, 0xbfb8aa3b, v61
	v_exp_f32_e32 v64, v64
	v_exp_f32_e32 v65, v65
	v_mul_f32_e32 v66, 0xbfb8aa3b, v62
	v_mul_f32_e32 v67, 0xbfb8aa3b, v63
	v_exp_f32_e32 v66, v66
	v_exp_f32_e32 v67, v67
	v_add_f32_e32 v64, 1.0, v64
	v_add_f32_e32 v65, 1.0, v65
	v_rcp_f32_e32 v64, v64
	v_rcp_f32_e32 v65, v65
	v_add_f32_e32 v66, 1.0, v66
	v_add_f32_e32 v67, 1.0, v67
	v_rcp_f32_e32 v66, v66
	v_rcp_f32_e32 v67, v67
	v_pk_mul_f32 v[60:61], v[60:61], v[64:65]
	v_pk_add_f32 v[56:57], v[56:57], 0 op_sel_hi:[1,0]
	v_pk_mul_f32 v[52:53], v[60:61], v[52:53]
	v_pk_mul_f32 v[60:61], v[62:63], v[66:67]
	v_mul_f32_e32 v62, 0xbfb8aa3b, v56
	v_exp_f32_e32 v62, v62
	v_pk_add_f32 v[54:55], v[54:55], 0 op_sel_hi:[1,0]
	v_pk_add_f32 v[58:59], v[58:59], 0 op_sel_hi:[1,0]
	v_pk_mul_f32 v[54:55], v[60:61], v[54:55]
	v_mul_f32_e32 v60, 0xbfb8aa3b, v57
	v_exp_f32_e32 v61, v60
	v_add_f32_e32 v60, 1.0, v62
	v_mul_f32_e32 v62, 0xbfb8aa3b, v58
	v_mul_f32_e32 v63, 0xbfb8aa3b, v59
	v_exp_f32_e32 v62, v62
	v_exp_f32_e32 v63, v63
	v_add_f32_e32 v61, 1.0, v61
	v_rcp_f32_e32 v60, v60
	v_rcp_f32_e32 v61, v61
	v_add_f32_e32 v62, 1.0, v62
	v_add_f32_e32 v63, 1.0, v63
	v_rcp_f32_e32 v62, v62
	v_rcp_f32_e32 v63, v63
	v_pk_add_f32 v[48:49], v[48:49], 0 op_sel_hi:[1,0]
	v_pk_mul_f32 v[56:57], v[56:57], v[60:61]
	v_add_u32_e32 v68, 0x80, v150
	v_pk_mul_f32 v[56:57], v[56:57], v[48:49]
	v_pk_add_f32 v[48:49], v[50:51], 0 op_sel_hi:[1,0]
	v_pk_mul_f32 v[50:51], v[58:59], v[62:63]
	v_pk_add_f32 v[44:45], v[44:45], 0 op_sel_hi:[1,0]
	v_pk_mul_f32 v[58:59], v[50:51], v[48:49]
	v_cvt_pk_bf16_f32 v48, v52, v53
	v_mad_i64_i32 v[52:53], s[28:29], v68, s56, v[112:113]
	v_cvt_pk_bf16_f32 v49, v54, v55
	v_cvt_pk_bf16_f32 v50, v56, v57
	v_cvt_pk_bf16_f32 v51, v58, v59
	v_lshl_add_u64 v[52:53], v[52:53], 0, v[114:115]
	v_mul_f32_e32 v54, 0xbfb8aa3b, v44
	global_store_dwordx4 v[52:53], v[48:51], off
	v_pk_add_f32 v[46:47], v[46:47], 0 op_sel_hi:[1,0]
	v_exp_f32_e32 v54, v54
	v_mul_f32_e32 v48, 0xbfb8aa3b, v45
	v_exp_f32_e32 v49, v48
	v_mul_f32_e32 v50, 0xbfb8aa3b, v46
	v_mul_f32_e32 v51, 0xbfb8aa3b, v47
	v_exp_f32_e32 v50, v50
	v_exp_f32_e32 v51, v51
	v_add_f32_e32 v48, 1.0, v54
	v_add_f32_e32 v49, 1.0, v49
	v_rcp_f32_e32 v48, v48
	v_rcp_f32_e32 v49, v49
	v_add_f32_e32 v50, 1.0, v50
	v_add_f32_e32 v51, 1.0, v51
	v_rcp_f32_e32 v50, v50
	v_rcp_f32_e32 v51, v51
	v_pk_add_f32 v[36:37], v[36:37], 0 op_sel_hi:[1,0]
	v_pk_mul_f32 v[44:45], v[44:45], v[48:49]
	v_pk_add_f32 v[40:41], v[40:41], 0 op_sel_hi:[1,0]
	v_pk_mul_f32 v[36:37], v[44:45], v[36:37]
	v_pk_mul_f32 v[44:45], v[46:47], v[50:51]
	v_mul_f32_e32 v46, 0xbfb8aa3b, v40
	v_exp_f32_e32 v46, v46
	v_pk_add_f32 v[38:39], v[38:39], 0 op_sel_hi:[1,0]
	v_pk_add_f32 v[42:43], v[42:43], 0 op_sel_hi:[1,0]
	v_pk_mul_f32 v[38:39], v[44:45], v[38:39]
	v_mul_f32_e32 v44, 0xbfb8aa3b, v41
	v_exp_f32_e32 v45, v44
	v_add_f32_e32 v44, 1.0, v46
	v_mul_f32_e32 v46, 0xbfb8aa3b, v42
	v_mul_f32_e32 v47, 0xbfb8aa3b, v43
	v_exp_f32_e32 v46, v46
	v_exp_f32_e32 v47, v47
	v_add_f32_e32 v45, 1.0, v45
	v_rcp_f32_e32 v44, v44
	v_rcp_f32_e32 v45, v45
	v_add_f32_e32 v46, 1.0, v46
	v_add_f32_e32 v47, 1.0, v47
	v_rcp_f32_e32 v46, v46
	v_rcp_f32_e32 v47, v47
	v_pk_add_f32 v[32:33], v[32:33], 0 op_sel_hi:[1,0]
	v_pk_mul_f32 v[40:41], v[40:41], v[44:45]
	v_add_u32_e32 v44, 0x90, v150
	v_pk_mul_f32 v[40:41], v[40:41], v[32:33]
	v_pk_add_f32 v[32:33], v[34:35], 0 op_sel_hi:[1,0]
	v_pk_mul_f32 v[34:35], v[42:43], v[46:47]
	v_pk_add_f32 v[28:29], v[28:29], 0 op_sel_hi:[1,0]
	v_pk_mul_f32 v[42:43], v[34:35], v[32:33]
	v_cvt_pk_bf16_f32 v32, v36, v37
	v_mad_i64_i32 v[36:37], s[28:29], v44, s56, v[112:113]
	v_cvt_pk_bf16_f32 v33, v38, v39
	v_cvt_pk_bf16_f32 v34, v40, v41
	v_cvt_pk_bf16_f32 v35, v42, v43
	v_lshl_add_u64 v[36:37], v[36:37], 0, v[114:115]
	v_mul_f32_e32 v38, 0xbfb8aa3b, v28
	global_store_dwordx4 v[36:37], v[32:35], off
	v_pk_add_f32 v[30:31], v[30:31], 0 op_sel_hi:[1,0]
	v_exp_f32_e32 v38, v38
	v_mul_f32_e32 v32, 0xbfb8aa3b, v29
	v_exp_f32_e32 v33, v32
	v_mul_f32_e32 v34, 0xbfb8aa3b, v30
	v_mul_f32_e32 v35, 0xbfb8aa3b, v31
	v_exp_f32_e32 v34, v34
	v_exp_f32_e32 v35, v35
	v_add_f32_e32 v32, 1.0, v38
	v_add_f32_e32 v33, 1.0, v33
	v_rcp_f32_e32 v32, v32
	v_rcp_f32_e32 v33, v33
	v_add_f32_e32 v34, 1.0, v34
	v_add_f32_e32 v35, 1.0, v35
	v_rcp_f32_e32 v34, v34
	v_rcp_f32_e32 v35, v35
	v_pk_add_f32 v[20:21], v[20:21], 0 op_sel_hi:[1,0]
	v_pk_mul_f32 v[28:29], v[28:29], v[32:33]
	v_pk_add_f32 v[24:25], v[24:25], 0 op_sel_hi:[1,0]
	v_pk_mul_f32 v[20:21], v[28:29], v[20:21]
	v_pk_mul_f32 v[28:29], v[30:31], v[34:35]
	v_mul_f32_e32 v30, 0xbfb8aa3b, v24
	v_exp_f32_e32 v30, v30
	v_pk_add_f32 v[22:23], v[22:23], 0 op_sel_hi:[1,0]
	v_pk_add_f32 v[26:27], v[26:27], 0 op_sel_hi:[1,0]
	v_pk_mul_f32 v[22:23], v[28:29], v[22:23]
	v_mul_f32_e32 v28, 0xbfb8aa3b, v25
	v_exp_f32_e32 v29, v28
	v_add_f32_e32 v28, 1.0, v30
	v_mul_f32_e32 v30, 0xbfb8aa3b, v26
	v_mul_f32_e32 v31, 0xbfb8aa3b, v27
	v_exp_f32_e32 v30, v30
	v_exp_f32_e32 v31, v31
	v_add_f32_e32 v29, 1.0, v29
	v_rcp_f32_e32 v28, v28
	v_rcp_f32_e32 v29, v29
	v_add_f32_e32 v30, 1.0, v30
	v_add_f32_e32 v31, 1.0, v31
	v_rcp_f32_e32 v30, v30
	v_rcp_f32_e32 v31, v31
	v_pk_add_f32 v[16:17], v[16:17], 0 op_sel_hi:[1,0]
	v_pk_mul_f32 v[24:25], v[24:25], v[28:29]
	v_add_u32_e32 v28, 0xa0, v150
	v_pk_mul_f32 v[24:25], v[24:25], v[16:17]
	v_pk_add_f32 v[16:17], v[18:19], 0 op_sel_hi:[1,0]
	v_pk_mul_f32 v[18:19], v[26:27], v[30:31]
	v_pk_add_f32 v[12:13], v[12:13], 0 op_sel_hi:[1,0]
	v_pk_mul_f32 v[26:27], v[18:19], v[16:17]
	v_cvt_pk_bf16_f32 v16, v20, v21
	v_mad_i64_i32 v[20:21], s[28:29], v28, s56, v[112:113]
	v_cvt_pk_bf16_f32 v17, v22, v23
	v_cvt_pk_bf16_f32 v18, v24, v25
	v_cvt_pk_bf16_f32 v19, v26, v27
	v_lshl_add_u64 v[20:21], v[20:21], 0, v[114:115]
	v_mul_f32_e32 v22, 0xbfb8aa3b, v12
	global_store_dwordx4 v[20:21], v[16:19], off
	v_pk_add_f32 v[14:15], v[14:15], 0 op_sel_hi:[1,0]
	v_exp_f32_e32 v22, v22
	v_mul_f32_e32 v16, 0xbfb8aa3b, v13
	v_exp_f32_e32 v17, v16
	v_mul_f32_e32 v18, 0xbfb8aa3b, v14
	v_mul_f32_e32 v19, 0xbfb8aa3b, v15
	v_exp_f32_e32 v18, v18
	v_exp_f32_e32 v19, v19
	v_add_f32_e32 v16, 1.0, v22
	v_add_f32_e32 v17, 1.0, v17
	v_rcp_f32_e32 v16, v16
	v_rcp_f32_e32 v17, v17
	v_add_f32_e32 v18, 1.0, v18
	v_add_f32_e32 v19, 1.0, v19
	v_rcp_f32_e32 v18, v18
	v_rcp_f32_e32 v19, v19
	v_pk_add_f32 v[4:5], v[4:5], 0 op_sel_hi:[1,0]
	v_pk_mul_f32 v[12:13], v[12:13], v[16:17]
	v_pk_add_f32 v[8:9], v[8:9], 0 op_sel_hi:[1,0]
	v_pk_mul_f32 v[4:5], v[12:13], v[4:5]
	v_pk_mul_f32 v[12:13], v[14:15], v[18:19]
	v_mul_f32_e32 v14, 0xbfb8aa3b, v8
	v_exp_f32_e32 v14, v14
	v_pk_add_f32 v[6:7], v[6:7], 0 op_sel_hi:[1,0]
	v_pk_add_f32 v[10:11], v[10:11], 0 op_sel_hi:[1,0]
	v_pk_mul_f32 v[6:7], v[12:13], v[6:7]
	v_mul_f32_e32 v12, 0xbfb8aa3b, v9
	v_exp_f32_e32 v13, v12
	v_add_f32_e32 v12, 1.0, v14
	v_mul_f32_e32 v14, 0xbfb8aa3b, v10
	v_mul_f32_e32 v15, 0xbfb8aa3b, v11
	v_exp_f32_e32 v14, v14
	v_exp_f32_e32 v15, v15
	v_add_f32_e32 v13, 1.0, v13
	v_rcp_f32_e32 v12, v12
	v_rcp_f32_e32 v13, v13
	v_add_f32_e32 v14, 1.0, v14
	v_add_f32_e32 v15, 1.0, v15
	v_rcp_f32_e32 v14, v14
	v_rcp_f32_e32 v15, v15
	v_pk_add_f32 v[0:1], v[0:1], 0 op_sel_hi:[1,0]
	v_pk_mul_f32 v[8:9], v[8:9], v[12:13]
	v_add_u32_e32 v12, 0xb0, v150
	v_pk_mul_f32 v[8:9], v[8:9], v[0:1]
	v_pk_add_f32 v[0:1], v[2:3], 0 op_sel_hi:[1,0]
	v_pk_mul_f32 v[2:3], v[10:11], v[14:15]
	s_and_b64 vcc, exec, s[16:17]
	v_pk_mul_f32 v[10:11], v[2:3], v[0:1]
	v_cvt_pk_bf16_f32 v0, v4, v5
	v_mad_i64_i32 v[4:5], s[28:29], v12, s56, v[112:113]
	v_cvt_pk_bf16_f32 v1, v6, v7
	v_cvt_pk_bf16_f32 v2, v8, v9
	v_cvt_pk_bf16_f32 v3, v10, v11
	v_lshl_add_u64 v[4:5], v[4:5], 0, v[114:115]
	s_mov_b32 s57, s10
	s_mov_b32 s30, s12
	s_mov_b64 s[36:37], s[18:19]
	s_mov_b64 s[34:35], s[14:15]
	global_store_dwordx4 v[4:5], v[0:3], off
	s_cbranch_vccz .LBB0_1198
	s_branch .LBB0_1206
